# MoBA QK: all 16 K-fragment LDS reads issued up front with counted lgkmcnt waits (was read-wait-2xMFMA serial chain)
# speedup vs baseline: 1.0166x; 1.0053x over previous
.LBB0_899:
	s_add_i32 s40, s85, 0xffffff00
	s_and_b64 s[38:39], s[38:39], exec
	s_mul_i32 s38, s86, 0x4400
	v_add_u32_e32 v154, s38, v192
	ds_read_b128 v[116:119], v154
	ds_read_b128 v[120:123], v154 offset:4352
	ds_read_b128 v[124:127], v154 offset:8704
	ds_read_b128 v[128:131], v154 offset:13056
	ds_read_b128 v[194:197], v154 offset:64
	ds_read_b128 v[198:201], v154 offset:4416
	ds_read_b128 v[202:205], v154 offset:8768
	ds_read_b128 v[206:209], v154 offset:13120
	ds_read_b128 v[226:229], v154 offset:128
	ds_read_b128 v[230:233], v154 offset:4480
	ds_read_b128 v[234:237], v154 offset:8832
	ds_read_b128 v[238:241], v154 offset:13184
	ds_read_b128 v[242:245], v154 offset:192
	ds_read_b128 v[246:249], v154 offset:4544
	s_cselect_b32 s40, s44, s40
	s_mov_b64 s[38:39], -1
	s_and_b64 vcc, exec, s[4:5]
	s_waitcnt lgkmcnt(13)
	v_mfma_f32_16x16x32_bf16 v[132:135], v[116:119], v[92:95], 0
	v_mfma_f32_16x16x32_bf16 v[116:119], v[116:119], v[96:99], 0
	s_waitcnt lgkmcnt(12)
	v_mfma_f32_16x16x32_bf16 v[136:139], v[120:123], v[92:95], 0
	v_mfma_f32_16x16x32_bf16 v[120:123], v[120:123], v[96:99], 0
	s_waitcnt lgkmcnt(11)
	v_mfma_f32_16x16x32_bf16 v[140:143], v[124:127], v[92:95], 0
	v_mfma_f32_16x16x32_bf16 v[124:127], v[124:127], v[96:99], 0
	s_waitcnt lgkmcnt(10)
	v_mfma_f32_16x16x32_bf16 v[144:147], v[128:131], v[92:95], 0
	v_mfma_f32_16x16x32_bf16 v[128:131], v[128:131], v[96:99], 0
	s_waitcnt lgkmcnt(9)
	v_mfma_f32_16x16x32_bf16 v[132:135], v[194:197], v[84:87], v[132:135]
	v_mfma_f32_16x16x32_bf16 v[116:119], v[194:197], v[88:91], v[116:119]
	ds_read_b128 v[194:197], v154 offset:8896
	s_waitcnt lgkmcnt(9)
	v_mfma_f32_16x16x32_bf16 v[136:139], v[198:201], v[84:87], v[136:139]
	v_mfma_f32_16x16x32_bf16 v[120:123], v[198:201], v[88:91], v[120:123]
	ds_read_b128 v[198:201], v154 offset:13248
	s_waitcnt lgkmcnt(9)
	v_mfma_f32_16x16x32_bf16 v[140:143], v[202:205], v[84:87], v[140:143]
	v_mfma_f32_16x16x32_bf16 v[124:127], v[202:205], v[88:91], v[124:127]
	s_waitcnt lgkmcnt(8)
	v_mfma_f32_16x16x32_bf16 v[144:147], v[206:209], v[84:87], v[144:147]
	v_mfma_f32_16x16x32_bf16 v[128:131], v[206:209], v[88:91], v[128:131]
	s_waitcnt lgkmcnt(7)
	v_mfma_f32_16x16x32_bf16 v[132:135], v[226:229], v[76:79], v[132:135]
	v_mfma_f32_16x16x32_bf16 v[116:119], v[226:229], v[80:83], v[116:119]
	s_waitcnt lgkmcnt(6)
	v_mfma_f32_16x16x32_bf16 v[136:139], v[230:233], v[76:79], v[136:139]
	v_mfma_f32_16x16x32_bf16 v[120:123], v[230:233], v[80:83], v[120:123]
	s_waitcnt lgkmcnt(5)
	v_mfma_f32_16x16x32_bf16 v[140:143], v[234:237], v[76:79], v[140:143]
	v_mfma_f32_16x16x32_bf16 v[124:127], v[234:237], v[80:83], v[124:127]
	s_waitcnt lgkmcnt(4)
	v_mfma_f32_16x16x32_bf16 v[144:147], v[238:241], v[76:79], v[144:147]
	v_mfma_f32_16x16x32_bf16 v[128:131], v[238:241], v[80:83], v[128:131]
	s_waitcnt lgkmcnt(3)
	v_mfma_f32_16x16x32_bf16 v[132:135], v[242:245], v[68:71], v[132:135]
	v_mfma_f32_16x16x32_bf16 v[116:119], v[242:245], v[72:75], v[116:119]
	s_waitcnt lgkmcnt(2)
	v_mfma_f32_16x16x32_bf16 v[136:139], v[246:249], v[68:71], v[136:139]
	v_mfma_f32_16x16x32_bf16 v[120:123], v[246:249], v[72:75], v[120:123]
	s_waitcnt lgkmcnt(1)
	v_mfma_f32_16x16x32_bf16 v[140:143], v[194:197], v[68:71], v[140:143]
	v_mfma_f32_16x16x32_bf16 v[124:127], v[194:197], v[72:75], v[124:127]
	s_waitcnt lgkmcnt(0)
	v_mfma_f32_16x16x32_bf16 v[144:147], v[198:201], v[68:71], v[144:147]
	v_mfma_f32_16x16x32_bf16 v[128:131], v[198:201], v[72:75], v[128:131]
	s_cbranch_vccz .LBB0_903
	v_and_b32_e32 v154, v8, v190
	v_cmp_eq_u32_e32 vcc, 0, v154
	v_mov_b32_e32 v195, v135
	v_mov_b32_e32 v200, v134
	v_mov_b32_e32 v204, v133
	v_mov_b32_e32 v208, v132
	v_mov_b32_e32 v196, v139
	v_mov_b32_e32 v199, v138
	v_mov_b32_e32 v203, v137
	v_mov_b32_e32 v207, v136
	v_mov_b32_e32 v194, v143
	v_mov_b32_e32 v197, v142
	v_mov_b32_e32 v202, v141
	v_mov_b32_e32 v206, v140
	v_mov_b32_e32 v198, v147
	v_mov_b32_e32 v201, v146
	v_mov_b32_e32 v205, v145
	v_mov_b32_e32 v209, v144
	s_and_saveexec_b64 s[38:39], vcc
	s_cbranch_execz .LBB0_902
	v_mov_b32_e32 v195, 0xff800000
	v_mov_b32_e32 v200, 0xff800000
	v_mov_b32_e32 v204, 0xff800000
	v_mov_b32_e32 v208, 0xff800000
	v_mov_b32_e32 v196, 0xff800000
	v_mov_b32_e32 v199, 0xff800000
	v_mov_b32_e32 v203, 0xff800000
	v_mov_b32_e32 v207, 0xff800000
	v_mov_b32_e32 v194, 0xff800000
	v_mov_b32_e32 v197, 0xff800000
	v_mov_b32_e32 v202, 0xff800000
	v_mov_b32_e32 v206, 0xff800000
	v_mov_b32_e32 v198, 0xff800000
	v_mov_b32_e32 v201, 0xff800000
	v_mov_b32_e32 v205, 0xff800000
	v_mov_b32_e32 v209, 0xff800000
